# P4 item loop software-pipelined across items: the next item's Qx / S_n k-blocks 1..3 / Oloc loads (36 of 52) are issued before the current item's norm-gate tail
# speedup vs baseline: 1.0036x; 1.0028x over previous
; #define GAS __attribute__((address_space(1)))
; __device__ __forceinline__ unsigned long long rt() { return __builtin_amdgcn_s_memrealtime(); }
; __device__ __forceinline__ void p4_load_a(P4Pre& P, const P4Ptr& p, int lane) {
;     const int r = lane & 15, g = lane >> 4, t = 16 * p.mt + r;
; #pragma unroll
;     for (int kb = 0; kb < 4; ++kb) P.ya[kb] = *(const GAS bf16x8*)(p.region + (size_t)((p.mt * 4 + kb) * 64 + lane) * 8);
; #pragma unroll
;     for (int vt = 0; vt < 4; ++vt)
; #pragma unroll
;         for (int kb = 0; kb < 4; ++kb) P.x[vt][kb] = *(const GAS bf16x8*)(p.sn + (size_t)((vt * 4 + kb) * 64 + lane) * 8);
; #pragma unroll
;     for (int vt = 0; vt < 8; ++vt) { P.ol[vt] = *(const GAS u64_t*)(p.oloc + (size_t)((vt * 4 + p.mt) * 64 + lane) * 4); P.gt8[vt] = *(const GAS u64_t*)(p.region + 24576 + t * 128 + 16 * vt + 4 * g); }
; }
; __device__ __forceinline__ void p4_run(int gw, int NGW, const bf16_t* HGR, const bf16_t* DNR, const bf16_t* OLH, const bf16_t* OLD, const bf16_t* BNB, const float* hg_nw, const float* dn_nw, bf16_t* OAB, int lane) {
;     const int r = lane & 15, g = lane >> 4;
;     P4Pre P; P4Ptr p = p4_ptrs(gw, HGR, DNR, OLH, OLD, BNB, hg_nw, dn_nw);
;     if (gw < 8192) p4_load_a(P, p, lane);
; __global__ void __launch_bounds__(NWAVES * 64, 2) fwd(Args args) {
;     ...
;     if (IN(4)) {
;         const unsigned long long amp_t0_4 = (PROBE_AMP == 4) ? rt() : 0ull;
;         _Pragma("unroll 1") for (int rep_ = 0; rep_ < ((PROBE == 4) ? 2 : 1); ++rep_) {
;         const int gw = (int)blockIdx.x * NWAVES + wave, NGW = G * NWAVES;
;         p4_run(gw, NGW, HGR, DNR, OLH, OLD, BNB, args.in[4], args.in[7], OAB, lane);
.LBB0_890:
	s_add_u32 s10, s60, 0xa004000
	s_addc_u32 s11, s61, 0
	s_add_u32 s8, s60, 0xe000000
	s_addc_u32 s9, s61, 0
	s_cmp_lt_i32 s56, 5
	s_cselect_b64 s[0:1], -1, 0
	s_cmp_gt_i32 s57, 4
	s_cselect_b64 s[4:5], -1, 0
	s_and_b64 s[0:1], s[0:1], s[4:5]
	s_andn2_b64 vcc, exec, s[0:1]
	s_cbranch_vccnz .LBB0_946
	s_and_b32 s4, s72, 56
	s_and_b32 s0, s73, 7
	s_or_b32 s4, s4, s0
	s_lshl_b32 s4, s4, 6
	s_lshr_b32 s0, s2, 6
	s_lshl_b32 s0, s0, 3
	s_add_i32 s4, s4, s0
	s_add_i32 s4, s4, s48
	s_cmpk_gt_i32 s4, 0x1fff
	s_cbranch_scc1 .LBB0_896
	s_waitcnt vmcnt(0)
	s_bfe_u32 s38, s66, 0x20006
	v_lshlrev_b32_e32 v210, 4, v234
	v_and_b32_e32 v211, 15, v234
	v_lshrrev_b32_e32 v212, 4, v234
	v_lshlrev_b32_e32 v213, 8, v211
	v_lshl_or_b32 v213, v212, 3, v213
	v_and_b32_e32 v214, 1, v212
	v_lshlrev_b32_e32 v214, 5, v214
	v_lshrrev_b32_e32 v215, 1, v212
	v_lshl_or_b32 v214, v215, 4, v214
	v_lshl_or_b32 v214, v211, 11, v214
	v_lshlrev_b32_e32 v215, 4, v212
	v_lshlrev_b32_e32 v216, 3, v234
	v_xor_b32_e32 v217, 16, v234
	v_lshlrev_b32_e32 v217, 2, v217
	v_xor_b32_e32 v218, 32, v234
	v_lshlrev_b32_e32 v218, 2, v218
	v_mov_b32_e32 v219, 0x358637bd
	s_bfe_u32 s36, s4, 0xa0002
	s_bfe_u32 s47, s4, 0x20002
	s_cmpk_lt_u32 s4, 0x1000
	s_cselect_b32 s6, s26, s62
	s_cselect_b32 s7, s27, s63
	s_lshl_b32 s3, s36, 16
	s_add_u32 s28, s6, s3
	s_addc_u32 s29, s7, 0
	s_add_u32 s40, s28, 0x4000
	s_addc_u32 s41, s29, 0
	s_lshl_b32 s3, s36, 15
	s_add_u32 s42, s64, s3
	s_addc_u32 s43, s65, 0
	s_cmpk_lt_u32 s4, 0x1000
	s_cselect_b32 s40, s40, s42
	s_cselect_b32 s41, s41, s43
	s_add_u32 s42, s60, 0xf000000
	s_addc_u32 s43, s61, 0
	s_cmpk_lt_u32 s4, 0x1000
	s_cselect_b32 s42, s8, s42
	s_cselect_b32 s43, s9, s43
	s_lshl_b32 s3, s36, 14
	s_add_u32 s42, s42, s3
	s_addc_u32 s43, s43, 0
	s_lshl_b32 s3, s38, 9
	s_add_u32 s42, s42, s3
	s_addc_u32 s43, s43, 0
	s_lshl_b32 s3, s47, 9
	s_add_u32 s44, s24, s3
	s_addc_u32 s45, s25, 0
	s_cmpk_lt_u32 s4, 0x1000
	s_cselect_b32 s44, s44, s30
	s_cselect_b32 s45, s45, s31
	s_lshl_b32 s3, s38, 12
	s_add_u32 s50, s28, s3
	s_addc_u32 s51, s29, 0
	s_add_u32 s18, s50, 0xc000
	s_addc_u32 s19, s51, 0
	s_lshr_b32 s3, s36, 2
	s_lshl_b32 s3, s3, 2
	s_or_b32 s3, s3, s38
	s_lshl_b32 s3, s3, 16
	s_add_u32 s68, s10, s3
	s_addc_u32 s69, s11, 0
	s_lshr_b32 s3, s4, 12
	s_lshl_b32 s3, s3, 10
	s_lshl_b32 s33, s47, 8
	s_or_b32 s3, s3, s33
	s_add_u32 s68, s68, s3
	s_addc_u32 s69, s69, 0
	s_mov_b64 s[74:75], s[40:41]
	global_load_dwordx4 v[2:5], v210, s[50:51]
	global_load_dwordx4 v[6:9], v210, s[50:51] offset:1024
	global_load_dwordx4 v[10:13], v210, s[50:51] offset:2048
	global_load_dwordx4 v[14:17], v210, s[50:51] offset:3072
	global_load_dwordx4 v[22:25], v210, s[40:41] offset:1024
	global_load_dwordx4 v[26:29], v210, s[40:41] offset:2048
	global_load_dwordx4 v[30:33], v210, s[40:41] offset:3072
	s_add_u32 s40, s40, 0x1000
	s_addc_u32 s41, s41, 0
	global_load_dwordx4 v[38:41], v210, s[40:41] offset:1024
	global_load_dwordx4 v[42:45], v210, s[40:41] offset:2048
	global_load_dwordx4 v[46:49], v210, s[40:41] offset:3072
	s_add_u32 s40, s40, 0x1000
	s_addc_u32 s41, s41, 0
	global_load_dwordx4 v[54:57], v210, s[40:41] offset:1024
	global_load_dwordx4 v[58:61], v210, s[40:41] offset:2048
	global_load_dwordx4 v[62:65], v210, s[40:41] offset:3072
	s_add_u32 s40, s40, 0x1000
	s_addc_u32 s41, s41, 0
	global_load_dwordx4 v[70:73], v210, s[40:41] offset:1024
	global_load_dwordx4 v[74:77], v210, s[40:41] offset:2048
	global_load_dwordx4 v[78:81], v210, s[40:41] offset:3072
	s_add_u32 s40, s40, 0x1000
	s_addc_u32 s41, s41, 0
	global_load_dwordx4 v[86:89], v210, s[40:41] offset:1024
	global_load_dwordx4 v[90:93], v210, s[40:41] offset:2048
	global_load_dwordx4 v[94:97], v210, s[40:41] offset:3072
	s_add_u32 s40, s40, 0x1000
	s_addc_u32 s41, s41, 0
	global_load_dwordx4 v[102:105], v210, s[40:41] offset:1024
	global_load_dwordx4 v[106:109], v210, s[40:41] offset:2048
	global_load_dwordx4 v[110:113], v210, s[40:41] offset:3072
	s_add_u32 s40, s40, 0x1000
	s_addc_u32 s41, s41, 0
	global_load_dwordx4 v[118:121], v210, s[40:41] offset:1024
	global_load_dwordx4 v[122:125], v210, s[40:41] offset:2048
	global_load_dwordx4 v[126:129], v210, s[40:41] offset:3072
	s_add_u32 s40, s40, 0x1000
	s_addc_u32 s41, s41, 0
	global_load_dwordx4 v[134:137], v210, s[40:41] offset:1024
	global_load_dwordx4 v[138:141], v210, s[40:41] offset:2048
	global_load_dwordx4 v[142:145], v210, s[40:41] offset:3072
	global_load_dwordx2 v[146:147], v216, s[42:43]
	global_load_dwordx2 v[148:149], v216, s[42:43] offset:2048
	s_add_u32 s42, s42, 0x1000
	s_addc_u32 s43, s43, 0
	global_load_dwordx2 v[150:151], v216, s[42:43]
	global_load_dwordx2 v[152:153], v216, s[42:43] offset:2048
	s_add_u32 s42, s42, 0x1000
	s_addc_u32 s43, s43, 0
	global_load_dwordx2 v[154:155], v216, s[42:43]
	global_load_dwordx2 v[156:157], v216, s[42:43] offset:2048
	s_add_u32 s42, s42, 0x1000
	s_addc_u32 s43, s43, 0
	global_load_dwordx2 v[158:159], v216, s[42:43]
	global_load_dwordx2 v[160:161], v216, s[42:43] offset:2048
; #define GAS __attribute__((address_space(1)))
; #define MFMA16(a, b, c) __builtin_amdgcn_mfma_f32_16x16x32_bf16((a), (b), (c), 0, 0, 0)
; __device__ __forceinline__ void p4_run(int gw, int NGW, const bf16_t* HGR, const bf16_t* DNR, const bf16_t* OLH, const bf16_t* OLD, const bf16_t* BNB, const float* hg_nw, const float* dn_nw, bf16_t* OAB, int lane) {
;     ...
;     for (int it = gw; it < 8192; it += NGW) {
;         asm volatile("" ::: "memory");
;         f32x4 o[8]; float ss = 0.f; u64_t gcur[8];
; #pragma unroll
;         for (int vt = 0; vt < 8; ++vt) gcur[vt] = P.gt8[vt];
; #pragma unroll
;         for (int vt = 0; vt < 4; ++vt) { f32x4 acc = unpack4(P.ol[vt]);
; #pragma unroll
;             for (int kb = 0; kb < 4; ++kb) acc = MFMA16(P.x[vt][kb], P.ya[kb], acc);
;             o[vt] = acc; ss += (acc[0] * acc[0] + acc[1] * acc[1]) + (acc[2] * acc[2] + acc[3] * acc[3]); }
;         asm volatile("" ::: "memory");
; #pragma unroll
;         for (int vt = 0; vt < 4; ++vt)
; #pragma unroll
;             for (int kb = 0; kb < 4; ++kb) P.x[vt][kb] = *(const GAS bf16x8*)(p.sn + (size_t)(((vt + 4) * 4 + kb) * 64 + lane) * 8);
;         f32x4 w8[8];
; #pragma unroll
;         for (int vt = 0; vt < 8; ++vt) w8[vt] = *(const GAS f32x4*)(p.nw + 16 * vt + 4 * g);
;         asm volatile("" ::: "memory");
; #pragma unroll
;         for (int vt = 0; vt < 4; ++vt) { f32x4 acc = unpack4(P.ol[vt + 4]);
; #pragma unroll
;             for (int kb = 0; kb < 4; ++kb) acc = MFMA16(P.x[vt][kb], P.ya[kb], acc);
;             o[vt + 4] = acc; ss += (acc[0] * acc[0] + acc[1] * acc[1]) + (acc[2] * acc[2] + acc[3] * acc[3]); }
;         const int t = 16 * p.mt + r;
;         bf16_t* orow2 = OAB + (size_t)(p.rb * 4 + p.mt) * 32768 + r * 1024 + p.br * 512 + p.h * 128 + 16 * (g & 1) + 8 * (g >> 1);
;         asm volatile("" :: "v"(o[4][0]), "v"(o[5][0]), "v"(o[6][0]), "v"(o[7][0]) : "memory");
;         if (it + NGW < 8192) { p = p4_ptrs(it + NGW, HGR, DNR, OLH, OLD, BNB, hg_nw, dn_nw); p4_load_a(P, p, lane); }
;         asm volatile("" ::: "memory");
;         ss += __shfl_xor(ss, 16); ss += __shfl_xor(ss, 32);
;         const float rstd = rsqrtf(ss * (1.f / 128.f) + RMS_EPS);
.Lp4n_item:
	global_load_dwordx4 v[18:21], v210, s[74:75]
	s_add_u32 s74, s74, 0x1000
	s_addc_u32 s75, s75, 0
	global_load_dwordx4 v[34:37], v210, s[74:75]
	s_add_u32 s74, s74, 0x1000
	s_addc_u32 s75, s75, 0
	global_load_dwordx4 v[50:53], v210, s[74:75]
	s_add_u32 s74, s74, 0x1000
	s_addc_u32 s75, s75, 0
	global_load_dwordx4 v[66:69], v210, s[74:75]
	s_add_u32 s74, s74, 0x1000
	s_addc_u32 s75, s75, 0
	global_load_dwordx4 v[82:85], v210, s[74:75]
	s_add_u32 s74, s74, 0x1000
	s_addc_u32 s75, s75, 0
	global_load_dwordx4 v[98:101], v210, s[74:75]
	s_add_u32 s74, s74, 0x1000
	s_addc_u32 s75, s75, 0
	global_load_dwordx4 v[114:117], v210, s[74:75]
	s_add_u32 s74, s74, 0x1000
	s_addc_u32 s75, s75, 0
	global_load_dwordx4 v[130:133], v210, s[74:75]
	global_load_dwordx2 v[162:163], v213, s[18:19]
	global_load_dwordx2 v[164:165], v213, s[18:19] offset:32
	global_load_dwordx2 v[166:167], v213, s[18:19] offset:64
	global_load_dwordx2 v[168:169], v213, s[18:19] offset:96
	global_load_dwordx2 v[170:171], v213, s[18:19] offset:128
	global_load_dwordx2 v[172:173], v213, s[18:19] offset:160
	global_load_dwordx2 v[174:175], v213, s[18:19] offset:192
	global_load_dwordx2 v[176:177], v213, s[18:19] offset:224
	s_waitcnt vmcnt(8)
	v_lshlrev_b32_e32 v178, 16, v146
	v_and_b32_e32 v179, 0xffff0000, v146
	v_lshlrev_b32_e32 v180, 16, v147
	v_and_b32_e32 v181, 0xffff0000, v147
	v_lshlrev_b32_e32 v182, 16, v148
	v_and_b32_e32 v183, 0xffff0000, v148
	v_lshlrev_b32_e32 v184, 16, v149
	v_and_b32_e32 v185, 0xffff0000, v149
	v_lshlrev_b32_e32 v186, 16, v150
	v_and_b32_e32 v187, 0xffff0000, v150
	v_lshlrev_b32_e32 v188, 16, v151
	v_and_b32_e32 v189, 0xffff0000, v151
	v_lshlrev_b32_e32 v190, 16, v152
	v_and_b32_e32 v191, 0xffff0000, v152
	v_lshlrev_b32_e32 v192, 16, v153
	v_and_b32_e32 v193, 0xffff0000, v153
	v_lshlrev_b32_e32 v194, 16, v154
	v_and_b32_e32 v195, 0xffff0000, v154
	v_lshlrev_b32_e32 v196, 16, v155
	v_and_b32_e32 v197, 0xffff0000, v155
	v_lshlrev_b32_e32 v198, 16, v156
	v_and_b32_e32 v199, 0xffff0000, v156
	v_lshlrev_b32_e32 v200, 16, v157
	v_and_b32_e32 v201, 0xffff0000, v157
	v_lshlrev_b32_e32 v202, 16, v158
	v_and_b32_e32 v203, 0xffff0000, v158
	v_lshlrev_b32_e32 v204, 16, v159
	v_and_b32_e32 v205, 0xffff0000, v159
	v_lshlrev_b32_e32 v206, 16, v160
	v_and_b32_e32 v207, 0xffff0000, v160
	v_lshlrev_b32_e32 v208, 16, v161
	v_and_b32_e32 v209, 0xffff0000, v161
	s_nop 1
	v_mfma_f32_16x16x32_bf16 v[178:181], v[18:21], v[2:5], v[178:181]
	v_mfma_f32_16x16x32_bf16 v[182:185], v[34:37], v[2:5], v[182:185]
	v_mfma_f32_16x16x32_bf16 v[186:189], v[50:53], v[2:5], v[186:189]
	v_mfma_f32_16x16x32_bf16 v[190:193], v[66:69], v[2:5], v[190:193]
	v_mfma_f32_16x16x32_bf16 v[194:197], v[82:85], v[2:5], v[194:197]
	v_mfma_f32_16x16x32_bf16 v[198:201], v[98:101], v[2:5], v[198:201]
	v_mfma_f32_16x16x32_bf16 v[202:205], v[114:117], v[2:5], v[202:205]
	v_mfma_f32_16x16x32_bf16 v[206:209], v[130:133], v[2:5], v[206:209]
	global_load_dwordx4 v[18:21], v215, s[44:45]
	global_load_dwordx4 v[34:37], v215, s[44:45] offset:64
	global_load_dwordx4 v[50:53], v215, s[44:45] offset:128
	global_load_dwordx4 v[66:69], v215, s[44:45] offset:192
	global_load_dwordx4 v[82:85], v215, s[44:45] offset:256
	global_load_dwordx4 v[98:101], v215, s[44:45] offset:320
	global_load_dwordx4 v[114:117], v215, s[44:45] offset:384
	global_load_dwordx4 v[130:133], v215, s[44:45] offset:448
	v_mfma_f32_16x16x32_bf16 v[178:181], v[22:25], v[6:9], v[178:181]
	v_mfma_f32_16x16x32_bf16 v[182:185], v[38:41], v[6:9], v[182:185]
	v_mfma_f32_16x16x32_bf16 v[186:189], v[54:57], v[6:9], v[186:189]
	v_mfma_f32_16x16x32_bf16 v[190:193], v[70:73], v[6:9], v[190:193]
	v_mfma_f32_16x16x32_bf16 v[194:197], v[86:89], v[6:9], v[194:197]
	v_mfma_f32_16x16x32_bf16 v[198:201], v[102:105], v[6:9], v[198:201]
	v_mfma_f32_16x16x32_bf16 v[202:205], v[118:121], v[6:9], v[202:205]
	v_mfma_f32_16x16x32_bf16 v[206:209], v[134:137], v[6:9], v[206:209]
	v_mfma_f32_16x16x32_bf16 v[178:181], v[26:29], v[10:13], v[178:181]
	v_mfma_f32_16x16x32_bf16 v[182:185], v[42:45], v[10:13], v[182:185]
	v_mfma_f32_16x16x32_bf16 v[186:189], v[58:61], v[10:13], v[186:189]
	v_mfma_f32_16x16x32_bf16 v[190:193], v[74:77], v[10:13], v[190:193]
	v_mfma_f32_16x16x32_bf16 v[194:197], v[90:93], v[10:13], v[194:197]
	v_mfma_f32_16x16x32_bf16 v[198:201], v[106:109], v[10:13], v[198:201]
	v_mfma_f32_16x16x32_bf16 v[202:205], v[122:125], v[10:13], v[202:205]
	v_mfma_f32_16x16x32_bf16 v[206:209], v[138:141], v[10:13], v[206:209]
	v_mfma_f32_16x16x32_bf16 v[178:181], v[30:33], v[14:17], v[178:181]
	v_mfma_f32_16x16x32_bf16 v[182:185], v[46:49], v[14:17], v[182:185]
	v_mfma_f32_16x16x32_bf16 v[186:189], v[62:65], v[14:17], v[186:189]
	v_mfma_f32_16x16x32_bf16 v[190:193], v[78:81], v[14:17], v[190:193]
	v_mfma_f32_16x16x32_bf16 v[194:197], v[94:97], v[14:17], v[194:197]
	v_mfma_f32_16x16x32_bf16 v[198:201], v[110:113], v[14:17], v[198:201]
	v_mfma_f32_16x16x32_bf16 v[202:205], v[126:129], v[14:17], v[202:205]
	v_mfma_f32_16x16x32_bf16 v[206:209], v[142:145], v[14:17], v[206:209]
	s_nop 7
	s_nop 3
	v_mul_f32_e32 v229, v179, v179
	v_mul_f32_e32 v230, v181, v181
	v_fmac_f32_e32 v229, v178, v178
	v_fmac_f32_e32 v230, v180, v180
	v_add_f32_e32 v229, v229, v230
	v_mov_b32_e32 v228, v229
	v_mul_f32_e32 v229, v183, v183
	v_mul_f32_e32 v230, v185, v185
	v_fmac_f32_e32 v229, v182, v182
	v_fmac_f32_e32 v230, v184, v184
	v_add_f32_e32 v229, v229, v230
	v_add_f32_e32 v228, v228, v229
	v_mul_f32_e32 v229, v187, v187
	v_mul_f32_e32 v230, v189, v189
	v_fmac_f32_e32 v229, v186, v186
	v_fmac_f32_e32 v230, v188, v188
	v_add_f32_e32 v229, v229, v230
	v_add_f32_e32 v228, v228, v229
	v_mul_f32_e32 v229, v191, v191
	v_mul_f32_e32 v230, v193, v193
	v_fmac_f32_e32 v229, v190, v190
	v_fmac_f32_e32 v230, v192, v192
	v_add_f32_e32 v229, v229, v230
	v_add_f32_e32 v228, v228, v229
	v_mul_f32_e32 v229, v195, v195
	v_mul_f32_e32 v230, v197, v197
	v_fmac_f32_e32 v229, v194, v194
	v_fmac_f32_e32 v230, v196, v196
	v_add_f32_e32 v229, v229, v230
	v_add_f32_e32 v228, v228, v229
	v_mul_f32_e32 v229, v199, v199
	v_mul_f32_e32 v230, v201, v201
	v_fmac_f32_e32 v229, v198, v198
	v_fmac_f32_e32 v230, v200, v200
	v_add_f32_e32 v229, v229, v230
	v_add_f32_e32 v228, v228, v229
	v_mul_f32_e32 v229, v203, v203
	v_mul_f32_e32 v230, v205, v205
	v_fmac_f32_e32 v229, v202, v202
	v_fmac_f32_e32 v230, v204, v204
	v_add_f32_e32 v229, v229, v230
	v_add_f32_e32 v228, v228, v229
	v_mul_f32_e32 v229, v207, v207
	v_mul_f32_e32 v230, v209, v209
	v_fmac_f32_e32 v229, v206, v206
	v_fmac_f32_e32 v230, v208, v208
	v_add_f32_e32 v229, v229, v230
	v_add_f32_e32 v228, v228, v229
	ds_bpermute_b32 v229, v217, v228
	s_waitcnt lgkmcnt(0)
	v_add_f32_e32 v228, v228, v229
	ds_bpermute_b32 v229, v218, v228
	s_waitcnt lgkmcnt(0)
	v_add_f32_e32 v228, v228, v229
	v_fmamk_f32 v228, v228, 0x3c000000, v219
	v_rsq_f32_e32 v232, v228
	v_mov_b32_e32 v233, 0
	s_bitcmp1_b32 s4, 5
	s_cselect_b32 s35, 0xfe0, 32
	s_add_i32 s4, s4, s35
	s_cmpk_gt_i32 s4, 0x1fff
	s_cbranch_scc1 .Lp4n_last
; #define GAS __attribute__((address_space(1)))
; __device__ __forceinline__ void p4_load_a(P4Pre& P, const P4Ptr& p, int lane) {
;     const int r = lane & 15, g = lane >> 4, t = 16 * p.mt + r;
; #pragma unroll
;     for (int kb = 0; kb < 4; ++kb) P.ya[kb] = *(const GAS bf16x8*)(p.region + (size_t)((p.mt * 4 + kb) * 64 + lane) * 8);
; #pragma unroll
;     for (int vt = 0; vt < 4; ++vt)
; #pragma unroll
;         for (int kb = 0; kb < 4; ++kb) P.x[vt][kb] = *(const GAS bf16x8*)(p.sn + (size_t)((vt * 4 + kb) * 64 + lane) * 8);
; #pragma unroll
;     for (int vt = 0; vt < 8; ++vt) { P.ol[vt] = *(const GAS u64_t*)(p.oloc + (size_t)((vt * 4 + p.mt) * 64 + lane) * 4); P.gt8[vt] = *(const GAS u64_t*)(p.region + 24576 + t * 128 + 16 * vt + 4 * g); }
; }
; __device__ __forceinline__ void p4_run(int gw, int NGW, const bf16_t* HGR, const bf16_t* DNR, const bf16_t* OLH, const bf16_t* OLD, const bf16_t* BNB, const float* hg_nw, const float* dn_nw, bf16_t* OAB, int lane) {
;     ...
;         if (it + NGW < 8192) { p = p4_ptrs(it + NGW, HGR, DNR, OLH, OLD, BNB, hg_nw, dn_nw); p4_load_a(P, p, lane); }
	s_bfe_u32 s36, s4, 0xa0002
	s_bfe_u32 s47, s4, 0x20002
	s_cmpk_lt_u32 s4, 0x1000
	s_cselect_b32 s6, s26, s62
	s_cselect_b32 s7, s27, s63
	s_lshl_b32 s3, s36, 16
	s_add_u32 s28, s6, s3
	s_addc_u32 s29, s7, 0
	s_add_u32 s40, s28, 0x4000
	s_addc_u32 s41, s29, 0
	s_lshl_b32 s3, s36, 15
	s_add_u32 s42, s64, s3
	s_addc_u32 s43, s65, 0
	s_cmpk_lt_u32 s4, 0x1000
	s_cselect_b32 s40, s40, s42
	s_cselect_b32 s41, s41, s43
	s_add_u32 s42, s60, 0xf000000
	s_addc_u32 s43, s61, 0
	s_cmpk_lt_u32 s4, 0x1000
	s_cselect_b32 s42, s8, s42
	s_cselect_b32 s43, s9, s43
	s_lshl_b32 s3, s36, 14
	s_add_u32 s42, s42, s3
	s_addc_u32 s43, s43, 0
	s_lshl_b32 s3, s38, 9
	s_add_u32 s42, s42, s3
	s_addc_u32 s43, s43, 0
	s_lshl_b32 s3, s47, 9
	s_add_u32 s44, s24, s3
	s_addc_u32 s45, s25, 0
	s_cmpk_lt_u32 s4, 0x1000
	s_cselect_b32 s44, s44, s30
	s_cselect_b32 s45, s45, s31
	s_lshl_b32 s3, s38, 12
	s_add_u32 s50, s28, s3
	s_addc_u32 s51, s29, 0
	s_add_u32 s18, s50, 0xc000
	s_addc_u32 s19, s51, 0
	s_lshr_b32 s3, s36, 2
	s_lshl_b32 s3, s3, 2
	s_or_b32 s3, s3, s38
	s_lshl_b32 s3, s3, 16
	s_add_u32 s70, s10, s3
	s_addc_u32 s71, s11, 0
	s_lshr_b32 s3, s4, 12
	s_lshl_b32 s3, s3, 10
	s_lshl_b32 s33, s47, 8
	s_or_b32 s3, s3, s33
	s_add_u32 s70, s70, s3
	s_addc_u32 s71, s71, 0
	s_mov_b64 s[74:75], s[40:41]
	global_load_dwordx4 v[2:5], v210, s[50:51]
	global_load_dwordx4 v[6:9], v210, s[50:51] offset:1024
	global_load_dwordx4 v[10:13], v210, s[50:51] offset:2048
	global_load_dwordx4 v[14:17], v210, s[50:51] offset:3072
	global_load_dwordx4 v[22:25], v210, s[40:41] offset:1024
	global_load_dwordx4 v[26:29], v210, s[40:41] offset:2048
	global_load_dwordx4 v[30:33], v210, s[40:41] offset:3072
	s_add_u32 s40, s40, 0x1000
	s_addc_u32 s41, s41, 0
	global_load_dwordx4 v[38:41], v210, s[40:41] offset:1024
	global_load_dwordx4 v[42:45], v210, s[40:41] offset:2048
	global_load_dwordx4 v[46:49], v210, s[40:41] offset:3072
	s_add_u32 s40, s40, 0x1000
	s_addc_u32 s41, s41, 0
	global_load_dwordx4 v[54:57], v210, s[40:41] offset:1024
	global_load_dwordx4 v[58:61], v210, s[40:41] offset:2048
	global_load_dwordx4 v[62:65], v210, s[40:41] offset:3072
	s_add_u32 s40, s40, 0x1000
	s_addc_u32 s41, s41, 0
	global_load_dwordx4 v[70:73], v210, s[40:41] offset:1024
	global_load_dwordx4 v[74:77], v210, s[40:41] offset:2048
	global_load_dwordx4 v[78:81], v210, s[40:41] offset:3072
	s_add_u32 s40, s40, 0x1000
	s_addc_u32 s41, s41, 0
	global_load_dwordx4 v[86:89], v210, s[40:41] offset:1024
	global_load_dwordx4 v[90:93], v210, s[40:41] offset:2048
	global_load_dwordx4 v[94:97], v210, s[40:41] offset:3072
	s_add_u32 s40, s40, 0x1000
	s_addc_u32 s41, s41, 0
	global_load_dwordx4 v[102:105], v210, s[40:41] offset:1024
	global_load_dwordx4 v[106:109], v210, s[40:41] offset:2048
	global_load_dwordx4 v[110:113], v210, s[40:41] offset:3072
	s_add_u32 s40, s40, 0x1000
	s_addc_u32 s41, s41, 0
	global_load_dwordx4 v[118:121], v210, s[40:41] offset:1024
	global_load_dwordx4 v[122:125], v210, s[40:41] offset:2048
	global_load_dwordx4 v[126:129], v210, s[40:41] offset:3072
	s_add_u32 s40, s40, 0x1000
	s_addc_u32 s41, s41, 0
	global_load_dwordx4 v[134:137], v210, s[40:41] offset:1024
	global_load_dwordx4 v[138:141], v210, s[40:41] offset:2048
	global_load_dwordx4 v[142:145], v210, s[40:41] offset:3072
	global_load_dwordx2 v[146:147], v216, s[42:43]
	global_load_dwordx2 v[148:149], v216, s[42:43] offset:2048
	s_add_u32 s42, s42, 0x1000
	s_addc_u32 s43, s43, 0
	global_load_dwordx2 v[150:151], v216, s[42:43]
	global_load_dwordx2 v[152:153], v216, s[42:43] offset:2048
	s_add_u32 s42, s42, 0x1000
	s_addc_u32 s43, s43, 0
	global_load_dwordx2 v[154:155], v216, s[42:43]
	global_load_dwordx2 v[156:157], v216, s[42:43] offset:2048
	s_add_u32 s42, s42, 0x1000
	s_addc_u32 s43, s43, 0
	global_load_dwordx2 v[158:159], v216, s[42:43]
	global_load_dwordx2 v[160:161], v216, s[42:43] offset:2048
	s_waitcnt vmcnt(36)
	s_branch .Lp4n_tail

; #define GAS __attribute__((address_space(1)))
; __device__ __forceinline__ u64_t pack4(const f32x4 v) { return (u64_t)pk2(v[0], v[1]) | ((u64_t)pk2(v[2], v[3]) << 32); }
; __device__ __forceinline__ void p4_run(int gw, int NGW, const bf16_t* HGR, const bf16_t* DNR, const bf16_t* OLH, const bf16_t* OLD, const bf16_t* BNB, const float* hg_nw, const float* dn_nw, bf16_t* OAB, int lane) {
;     ...
;         ss += __shfl_xor(ss, 16); ss += __shfl_xor(ss, 32);
;         const float rstd = rsqrtf(ss * (1.f / 128.f) + RMS_EPS);
; #pragma unroll
;         for (int p2 = 0; p2 < 4; ++p2) {
;             const u64_t X = pack4(o[2 * p2] * rstd * w8[2 * p2] * unpack4(gcur[2 * p2])), Y = pack4(o[2 * p2 + 1] * rstd * w8[2 * p2 + 1] * unpack4(gcur[2 * p2 + 1]));
;             const auto lo = __builtin_amdgcn_permlane16_swap((unsigned)X, (unsigned)Y, false, false), hi = __builtin_amdgcn_permlane16_swap((unsigned)(X >> 32), (unsigned)(Y >> 32), false, false);
;             *(GAS v4u*)(orow2 + 32 * p2) = (v4u){lo[0], hi[0], lo[1], hi[1]}; }
.Lp4n_tail:
	v_pk_mul_f32 v[178:179], v[178:179], v[232:233] op_sel_hi:[1,0]
	v_pk_mul_f32 v[180:181], v[180:181], v[232:233] op_sel_hi:[1,0]
	v_lshlrev_b32_e32 v220, 16, v162
	v_and_b32_e32 v221, 0xffff0000, v162
	v_lshlrev_b32_e32 v222, 16, v163
	v_and_b32_e32 v223, 0xffff0000, v163
	v_pk_mul_f32 v[178:179], v[18:19], v[178:179]
	v_pk_mul_f32 v[180:181], v[20:21], v[180:181]
	v_pk_mul_f32 v[178:179], v[178:179], v[220:221]
	v_pk_mul_f32 v[180:181], v[180:181], v[222:223]
	v_cvt_pk_bf16_f32 v224, v178, v179
	v_cvt_pk_bf16_f32 v225, v180, v181
	v_pk_mul_f32 v[182:183], v[182:183], v[232:233] op_sel_hi:[1,0]
	v_pk_mul_f32 v[184:185], v[184:185], v[232:233] op_sel_hi:[1,0]
	v_lshlrev_b32_e32 v220, 16, v164
	v_and_b32_e32 v221, 0xffff0000, v164
	v_lshlrev_b32_e32 v222, 16, v165
	v_and_b32_e32 v223, 0xffff0000, v165
	v_pk_mul_f32 v[182:183], v[34:35], v[182:183]
	v_pk_mul_f32 v[184:185], v[36:37], v[184:185]
	v_pk_mul_f32 v[182:183], v[182:183], v[220:221]
	v_pk_mul_f32 v[184:185], v[184:185], v[222:223]
	v_cvt_pk_bf16_f32 v226, v182, v183
	v_cvt_pk_bf16_f32 v227, v184, v185
	s_nop 1
	v_permlane16_swap_b32_e32 v224, v226
	v_permlane16_swap_b32_e32 v225, v227
	global_store_dwordx4 v214, v[224:227], s[68:69]
	s_nop 1
	v_pk_mul_f32 v[186:187], v[186:187], v[232:233] op_sel_hi:[1,0]
	v_pk_mul_f32 v[188:189], v[188:189], v[232:233] op_sel_hi:[1,0]
	v_lshlrev_b32_e32 v220, 16, v166
	v_and_b32_e32 v221, 0xffff0000, v166
	v_lshlrev_b32_e32 v222, 16, v167
	v_and_b32_e32 v223, 0xffff0000, v167
	v_pk_mul_f32 v[186:187], v[50:51], v[186:187]
	v_pk_mul_f32 v[188:189], v[52:53], v[188:189]
	v_pk_mul_f32 v[186:187], v[186:187], v[220:221]
	v_pk_mul_f32 v[188:189], v[188:189], v[222:223]
	v_cvt_pk_bf16_f32 v224, v186, v187
	v_cvt_pk_bf16_f32 v225, v188, v189
	v_pk_mul_f32 v[190:191], v[190:191], v[232:233] op_sel_hi:[1,0]
	v_pk_mul_f32 v[192:193], v[192:193], v[232:233] op_sel_hi:[1,0]
	v_lshlrev_b32_e32 v220, 16, v168
	v_and_b32_e32 v221, 0xffff0000, v168
	v_lshlrev_b32_e32 v222, 16, v169
	v_and_b32_e32 v223, 0xffff0000, v169
	v_pk_mul_f32 v[190:191], v[66:67], v[190:191]
	v_pk_mul_f32 v[192:193], v[68:69], v[192:193]
	v_pk_mul_f32 v[190:191], v[190:191], v[220:221]
	v_pk_mul_f32 v[192:193], v[192:193], v[222:223]
	v_cvt_pk_bf16_f32 v226, v190, v191
	v_cvt_pk_bf16_f32 v227, v192, v193
	s_nop 1
	v_permlane16_swap_b32_e32 v224, v226
	v_permlane16_swap_b32_e32 v225, v227
	global_store_dwordx4 v214, v[224:227], s[68:69] offset:64
	s_nop 1
	v_pk_mul_f32 v[194:195], v[194:195], v[232:233] op_sel_hi:[1,0]
	v_pk_mul_f32 v[196:197], v[196:197], v[232:233] op_sel_hi:[1,0]
	v_lshlrev_b32_e32 v220, 16, v170
	v_and_b32_e32 v221, 0xffff0000, v170
	v_lshlrev_b32_e32 v222, 16, v171
	v_and_b32_e32 v223, 0xffff0000, v171
	v_pk_mul_f32 v[194:195], v[82:83], v[194:195]
	v_pk_mul_f32 v[196:197], v[84:85], v[196:197]
	v_pk_mul_f32 v[194:195], v[194:195], v[220:221]
	v_pk_mul_f32 v[196:197], v[196:197], v[222:223]
	v_cvt_pk_bf16_f32 v224, v194, v195
	v_cvt_pk_bf16_f32 v225, v196, v197
	v_pk_mul_f32 v[198:199], v[198:199], v[232:233] op_sel_hi:[1,0]
	v_pk_mul_f32 v[200:201], v[200:201], v[232:233] op_sel_hi:[1,0]
	v_lshlrev_b32_e32 v220, 16, v172
	v_and_b32_e32 v221, 0xffff0000, v172
	v_lshlrev_b32_e32 v222, 16, v173
	v_and_b32_e32 v223, 0xffff0000, v173
	v_pk_mul_f32 v[198:199], v[98:99], v[198:199]
	v_pk_mul_f32 v[200:201], v[100:101], v[200:201]
	v_pk_mul_f32 v[198:199], v[198:199], v[220:221]
	v_pk_mul_f32 v[200:201], v[200:201], v[222:223]
	v_cvt_pk_bf16_f32 v226, v198, v199
	v_cvt_pk_bf16_f32 v227, v200, v201
	s_nop 1
	v_permlane16_swap_b32_e32 v224, v226
	v_permlane16_swap_b32_e32 v225, v227
	global_store_dwordx4 v214, v[224:227], s[68:69] offset:128
	s_nop 1
	v_pk_mul_f32 v[202:203], v[202:203], v[232:233] op_sel_hi:[1,0]
	v_pk_mul_f32 v[204:205], v[204:205], v[232:233] op_sel_hi:[1,0]
	v_lshlrev_b32_e32 v220, 16, v174
	v_and_b32_e32 v221, 0xffff0000, v174
	v_lshlrev_b32_e32 v222, 16, v175
	v_and_b32_e32 v223, 0xffff0000, v175
	v_pk_mul_f32 v[202:203], v[114:115], v[202:203]
	v_pk_mul_f32 v[204:205], v[116:117], v[204:205]
	v_pk_mul_f32 v[202:203], v[202:203], v[220:221]
	v_pk_mul_f32 v[204:205], v[204:205], v[222:223]
	v_cvt_pk_bf16_f32 v224, v202, v203
	v_cvt_pk_bf16_f32 v225, v204, v205
	v_pk_mul_f32 v[206:207], v[206:207], v[232:233] op_sel_hi:[1,0]
	v_pk_mul_f32 v[208:209], v[208:209], v[232:233] op_sel_hi:[1,0]
	v_lshlrev_b32_e32 v220, 16, v176
	v_and_b32_e32 v221, 0xffff0000, v176
	v_lshlrev_b32_e32 v222, 16, v177
	v_and_b32_e32 v223, 0xffff0000, v177
	v_pk_mul_f32 v[206:207], v[130:131], v[206:207]
	v_pk_mul_f32 v[208:209], v[132:133], v[208:209]
	v_pk_mul_f32 v[206:207], v[206:207], v[220:221]
	v_pk_mul_f32 v[208:209], v[208:209], v[222:223]
	v_cvt_pk_bf16_f32 v226, v206, v207
	v_cvt_pk_bf16_f32 v227, v208, v209
	s_nop 1
	v_permlane16_swap_b32_e32 v224, v226
	v_permlane16_swap_b32_e32 v225, v227
	global_store_dwordx4 v214, v[224:227], s[68:69] offset:192
	s_nop 1
	s_mov_b64 s[68:69], s[70:71]
	s_cmpk_gt_i32 s4, 0x1fff
	s_cbranch_scc0 .Lp4n_item
